# ctx-row GEMM K loop of the three FFN-out phases: 3-deep register prefetch (three chunk register sets, counted vmcnt ladders) on top of the S5 rewrite
# speedup vs baseline: 1.0491x; 1.0008x over previous
.LBB0_365:
	v_mov_b32_e32 v28, v176
	s_and_b32 s14, s21, 0x1e0
	v_add_u32_e32 v8, s1, v28
	s_and_b32 s15, s19, 0xffffffc0
	s_bitset1_b32 s14, 14
	s_sub_i32 s26, s15, 32
	v_lshlrev_b32_e32 v0, 4, v28
	v_ashrrev_i32_e32 v9, 5, v8
	v_and_b32_e32 v0, 0x1f0, v0
	v_mov_b32_e32 v10, s26
	v_mov_b32_e32 v11, s14
	v_cmp_gt_i32_e32 vcc, 32, v9
	v_lshl_add_u64 v[2:3], s[10:11], 0, v[0:1]
	v_lshl_add_u64 v[4:5], s[36:37], 0, v[0:1]
	v_cndmask_b32_e32 v6, v10, v11, vcc
	v_add_u32_e32 v12, v6, v9
	v_cndmask_b32_e32 v7, v3, v5, vcc
	v_cndmask_b32_e32 v6, v2, v4, vcc
	v_mad_i64_i32 v[18:19], s[26:27], v12, s22, v[6:7]
	v_add_u32_e32 v6, 0x200, v8
	v_ashrrev_i32_e32 v12, 5, v6
	v_cmp_gt_i32_e32 vcc, 32, v12
	v_add_u32_e32 v0, 0, v0
	s_or_b32 s15, s15, s17
	v_cndmask_b32_e32 v6, v10, v11, vcc
	v_add_u32_e32 v13, v6, v12
	v_cndmask_b32_e32 v7, v3, v5, vcc
	v_cndmask_b32_e32 v6, v2, v4, vcc
	v_mad_i64_i32 v[16:17], s[26:27], v13, s22, v[6:7]
	v_add_u32_e32 v6, 0x400, v8
	v_ashrrev_i32_e32 v13, 5, v6
	v_cmp_gt_i32_e32 vcc, 32, v13
	s_add_i32 s14, s14, s16
	s_nop 0
	v_cndmask_b32_e32 v6, v10, v11, vcc
	v_add_u32_e32 v14, v6, v13
	v_cndmask_b32_e32 v7, v3, v5, vcc
	v_cndmask_b32_e32 v6, v2, v4, vcc
	v_mad_i64_i32 v[20:21], s[26:27], v14, s22, v[6:7]
	v_add_u32_e32 v6, 0x600, v8
	v_ashrrev_i32_e32 v14, 5, v6
	v_cmp_gt_i32_e32 vcc, 32, v14
	s_nop 1
	v_cndmask_b32_e32 v6, v10, v11, vcc
	v_add_u32_e32 v15, v6, v14
	v_cndmask_b32_e32 v7, v3, v5, vcc
	v_cndmask_b32_e32 v6, v2, v4, vcc
	v_mad_i64_i32 v[22:23], s[26:27], v15, s22, v[6:7]
	v_add_u32_e32 v6, 0x800, v8
	v_ashrrev_i32_e32 v15, 5, v6
	v_cmp_gt_i32_e32 vcc, 32, v15
	s_nop 1
	v_cndmask_b32_e32 v6, v10, v11, vcc
	v_add_u32_e32 v24, v6, v15
	v_cndmask_b32_e32 v7, v3, v5, vcc
	v_cndmask_b32_e32 v6, v2, v4, vcc
	v_mad_i64_i32 v[24:25], s[26:27], v24, s22, v[6:7]
	v_add_u32_e32 v6, 0xa00, v8
	v_ashrrev_i32_e32 v29, 5, v6
	v_cmp_gt_i32_e32 vcc, 32, v29
	s_nop 1
	v_cndmask_b32_e32 v6, v10, v11, vcc
	v_add_u32_e32 v6, v6, v29
	v_cndmask_b32_e32 v3, v3, v5, vcc
	v_cndmask_b32_e32 v2, v2, v4, vcc
	v_mad_i64_i32 v[26:27], s[26:27], v6, s22, v[2:3]
	global_load_dwordx4 v[136:139], v[18:19], off
	global_load_dwordx4 v[140:143], v[16:17], off
	global_load_dwordx4 v[144:147], v[20:21], off
	global_load_dwordx4 v[148:151], v[22:23], off
	global_load_dwordx4 v[152:155], v[24:25], off
	global_load_dwordx4 v[156:159], v[26:27], off
	global_load_dwordx4 v[178:181], v[18:19], off offset:512
	global_load_dwordx4 v[182:185], v[16:17], off offset:512
	global_load_dwordx4 v[186:189], v[20:21], off offset:512
	global_load_dwordx4 v[190:193], v[22:23], off offset:512
	global_load_dwordx4 v[194:197], v[24:25], off offset:512
	global_load_dwordx4 v[198:201], v[26:27], off offset:512
	global_load_dwordx4 v[206:209], v[18:19], off offset:1024
	global_load_dwordx4 v[210:213], v[16:17], off offset:1024
	global_load_dwordx4 v[214:217], v[20:21], off offset:1024
	global_load_dwordx4 v[218:221], v[22:23], off offset:1024
	global_load_dwordx4 v[120:123], v[24:25], off offset:1024
	global_load_dwordx4 v[124:127], v[26:27], off offset:1024
	v_mov_b32_e32 v112, 0x1000
	v_mov_b32_e32 v113, 0
	v_lshl_add_u64 v[128:129], v[18:19], 0, v[112:113]
	v_lshl_add_u64 v[130:131], v[16:17], 0, v[112:113]
	v_lshl_add_u64 v[132:133], v[20:21], 0, v[112:113]
	v_lshl_add_u64 v[106:107], v[22:23], 0, v[112:113]
	v_lshl_add_u64 v[108:109], v[24:25], 0, v[112:113]
	v_lshl_add_u64 v[110:111], v[26:27], 0, v[112:113]
	v_mad_u64_u32 v[4:5], s[26:27], v9, s23, v[0:1]
	v_mad_u64_u32 v[6:7], s[26:27], v12, s23, v[0:1]
	v_mad_u64_u32 v[8:9], s[26:27], v13, s23, v[0:1]
	v_mad_u64_u32 v[10:11], s[26:27], v14, s23, v[0:1]
	v_mad_u64_u32 v[12:13], s[26:27], v15, s23, v[0:1]
	v_mad_u64_u32 v[14:15], s[26:27], v29, s23, v[0:1]
	s_barrier
	v_and_b32_e32 v0, 15, v28
	v_and_b32_e32 v2, -16, v28
	v_add_u32_e32 v2, 0, v2
	v_or_b32_e32 v5, s18, v0
	v_mad_u32_u24 v5, v5, s23, v2
	v_or_b32_e32 v3, s16, v0
	v_mad_u64_u32 v[2:3], s[26:27], v3, s23, v[2:3]
	v_ashrrev_i32_e32 v3, 2, v28
	v_and_b32_e32 v3, -4, v3
	v_or_b32_e32 v0, s14, v0
	s_waitcnt vmcnt(17)
	ds_write_b128 v4, v[136:139]
	s_waitcnt vmcnt(16)
	ds_write_b128 v6, v[140:143]
	s_waitcnt vmcnt(15)
	ds_write_b128 v8, v[144:147]
	s_waitcnt vmcnt(14)
	ds_write_b128 v10, v[148:151]
	s_waitcnt vmcnt(13)
	ds_write_b128 v12, v[152:155]
	s_waitcnt vmcnt(12)
	ds_write_b128 v14, v[156:159]
	s_waitcnt lgkmcnt(0)
	s_barrier
	global_load_dwordx4 v[136:139], v[18:19], off offset:1536
	global_load_dwordx4 v[140:143], v[16:17], off offset:1536
	global_load_dwordx4 v[144:147], v[20:21], off offset:1536
	global_load_dwordx4 v[148:151], v[22:23], off offset:1536
	global_load_dwordx4 v[152:155], v[24:25], off offset:1536
	global_load_dwordx4 v[156:159], v[26:27], off offset:1536
	ds_read_b128 v[54:57], v5
	ds_read_b128 v[58:61], v5 offset:64
	ds_read_b128 v[62:65], v2
	ds_read_b128 v[66:69], v2 offset:64
	s_waitcnt lgkmcnt(1)
	v_mfma_f32_16x16x32_f16 v[54:57], v[54:57], v[62:65], 0
	ds_read_b128 v[62:65], v5 offset:128
	ds_read_b128 v[70:73], v5 offset:192
	s_waitcnt lgkmcnt(2)
	v_mfma_f32_16x16x32_f16 v[54:57], v[58:61], v[66:69], v[54:57]
	ds_read_b128 v[58:61], v2 offset:128
	ds_read_b128 v[66:69], v2 offset:192
	s_waitcnt lgkmcnt(1)
	v_mfma_f32_16x16x32_f16 v[54:57], v[62:65], v[58:61], v[54:57]
	ds_read_b128 v[58:61], v5 offset:256
	ds_read_b128 v[62:65], v5 offset:320
	s_waitcnt lgkmcnt(2)
	v_mfma_f32_16x16x32_f16 v[54:57], v[70:73], v[66:69], v[54:57]
	ds_read_b128 v[66:69], v2 offset:256
	ds_read_b128 v[70:73], v2 offset:320
	ds_read_b128 v[74:77], v5 offset:384
	s_waitcnt lgkmcnt(2)
	v_mfma_f32_16x16x32_f16 v[54:57], v[58:61], v[66:69], v[54:57]
	ds_read_b128 v[58:61], v2 offset:384
	ds_read_b128 v[66:69], v2 offset:448
	ds_read_b128 v[78:81], v5 offset:448
	s_waitcnt lgkmcnt(0)
	s_barrier
	s_waitcnt vmcnt(17)
	ds_write_b128 v4, v[178:181]
	s_waitcnt vmcnt(16)
	ds_write_b128 v6, v[182:185]
	s_waitcnt vmcnt(15)
	ds_write_b128 v8, v[186:189]
	s_waitcnt vmcnt(14)
	ds_write_b128 v10, v[190:193]
	s_waitcnt vmcnt(13)
	ds_write_b128 v12, v[194:197]
	s_waitcnt vmcnt(12)
	ds_write_b128 v14, v[198:201]
	s_waitcnt lgkmcnt(0)
	s_barrier
	global_load_dwordx4 v[178:181], v[18:19], off offset:2048
	global_load_dwordx4 v[182:185], v[16:17], off offset:2048
	global_load_dwordx4 v[186:189], v[20:21], off offset:2048
	global_load_dwordx4 v[190:193], v[22:23], off offset:2048
	global_load_dwordx4 v[194:197], v[24:25], off offset:2048
	global_load_dwordx4 v[198:201], v[26:27], off offset:2048
	v_mfma_f32_16x16x32_f16 v[54:57], v[62:65], v[70:73], v[54:57]
	v_mfma_f32_16x16x32_f16 v[54:57], v[74:77], v[58:61], v[54:57]
	ds_read_b128 v[58:61], v5
	v_mfma_f32_16x16x32_f16 v[54:57], v[78:81], v[66:69], v[54:57]
	ds_read_b128 v[62:65], v5 offset:64
	ds_read_b128 v[66:69], v2
	ds_read_b128 v[70:73], v2 offset:64
	s_waitcnt lgkmcnt(1)
	v_mfma_f32_16x16x32_f16 v[54:57], v[58:61], v[66:69], v[54:57]
	ds_read_b128 v[58:61], v5 offset:128
	ds_read_b128 v[66:69], v5 offset:192
	s_waitcnt lgkmcnt(2)
	v_mfma_f32_16x16x32_f16 v[54:57], v[62:65], v[70:73], v[54:57]
	ds_read_b128 v[62:65], v2 offset:128
	ds_read_b128 v[70:73], v2 offset:192
	s_waitcnt lgkmcnt(1)
	v_mfma_f32_16x16x32_f16 v[54:57], v[58:61], v[62:65], v[54:57]
	ds_read_b128 v[58:61], v5 offset:256
	ds_read_b128 v[62:65], v5 offset:320
	s_waitcnt lgkmcnt(2)
	v_mfma_f32_16x16x32_f16 v[54:57], v[66:69], v[70:73], v[54:57]
	ds_read_b128 v[66:69], v2 offset:256
	ds_read_b128 v[70:73], v2 offset:320
	ds_read_b128 v[74:77], v5 offset:384
	s_waitcnt lgkmcnt(2)
	v_mfma_f32_16x16x32_f16 v[54:57], v[58:61], v[66:69], v[54:57]
	ds_read_b128 v[58:61], v2 offset:384
	ds_read_b128 v[66:69], v2 offset:448
	ds_read_b128 v[78:81], v5 offset:448
	s_waitcnt lgkmcnt(0)
	s_barrier
	s_waitcnt vmcnt(17)
	ds_write_b128 v4, v[206:209]
	s_waitcnt vmcnt(16)
	ds_write_b128 v6, v[210:213]
	s_waitcnt vmcnt(15)
	ds_write_b128 v8, v[214:217]
	s_waitcnt vmcnt(14)
	ds_write_b128 v10, v[218:221]
	s_waitcnt vmcnt(13)
	ds_write_b128 v12, v[120:123]
	s_waitcnt vmcnt(12)
	ds_write_b128 v14, v[124:127]
	s_waitcnt lgkmcnt(0)
	s_barrier
	global_load_dwordx4 v[206:209], v[18:19], off offset:2560
	global_load_dwordx4 v[210:213], v[16:17], off offset:2560
	global_load_dwordx4 v[214:217], v[20:21], off offset:2560
	global_load_dwordx4 v[218:221], v[22:23], off offset:2560
	global_load_dwordx4 v[120:123], v[24:25], off offset:2560
	global_load_dwordx4 v[124:127], v[26:27], off offset:2560
	v_mfma_f32_16x16x32_f16 v[54:57], v[62:65], v[70:73], v[54:57]
	v_mfma_f32_16x16x32_f16 v[54:57], v[74:77], v[58:61], v[54:57]
	ds_read_b128 v[58:61], v5
	v_mfma_f32_16x16x32_f16 v[54:57], v[78:81], v[66:69], v[54:57]
	ds_read_b128 v[62:65], v5 offset:64
	ds_read_b128 v[66:69], v2
	ds_read_b128 v[70:73], v2 offset:64
	s_waitcnt lgkmcnt(1)
	v_mfma_f32_16x16x32_f16 v[54:57], v[58:61], v[66:69], v[54:57]
	ds_read_b128 v[58:61], v5 offset:128
	ds_read_b128 v[66:69], v5 offset:192
	s_waitcnt lgkmcnt(2)
	v_mfma_f32_16x16x32_f16 v[54:57], v[62:65], v[70:73], v[54:57]
	ds_read_b128 v[62:65], v2 offset:128
	ds_read_b128 v[70:73], v2 offset:192
	s_waitcnt lgkmcnt(1)
	v_mfma_f32_16x16x32_f16 v[54:57], v[58:61], v[62:65], v[54:57]
	ds_read_b128 v[58:61], v5 offset:256
	ds_read_b128 v[62:65], v5 offset:320
	s_waitcnt lgkmcnt(2)
	v_mfma_f32_16x16x32_f16 v[54:57], v[66:69], v[70:73], v[54:57]
	ds_read_b128 v[66:69], v2 offset:256
	ds_read_b128 v[70:73], v2 offset:320
	ds_read_b128 v[74:77], v5 offset:384
	s_waitcnt lgkmcnt(2)
	v_mfma_f32_16x16x32_f16 v[54:57], v[58:61], v[66:69], v[54:57]
	ds_read_b128 v[58:61], v2 offset:384
	ds_read_b128 v[66:69], v2 offset:448
	ds_read_b128 v[78:81], v5 offset:448
	s_waitcnt lgkmcnt(0)
	s_barrier
	s_waitcnt vmcnt(17)
	ds_write_b128 v4, v[136:139]
	s_waitcnt vmcnt(16)
	ds_write_b128 v6, v[140:143]
	s_waitcnt vmcnt(15)
	ds_write_b128 v8, v[144:147]
	s_waitcnt vmcnt(14)
	ds_write_b128 v10, v[148:151]
	s_waitcnt vmcnt(13)
	ds_write_b128 v12, v[152:155]
	s_waitcnt vmcnt(12)
	ds_write_b128 v14, v[156:159]
	s_waitcnt lgkmcnt(0)
	s_barrier
	global_load_dwordx4 v[136:139], v[18:19], off offset:3072
	global_load_dwordx4 v[140:143], v[16:17], off offset:3072
	global_load_dwordx4 v[144:147], v[20:21], off offset:3072
	global_load_dwordx4 v[148:151], v[22:23], off offset:3072
	global_load_dwordx4 v[152:155], v[24:25], off offset:3072
	global_load_dwordx4 v[156:159], v[26:27], off offset:3072
	v_mfma_f32_16x16x32_f16 v[54:57], v[62:65], v[70:73], v[54:57]
	v_mfma_f32_16x16x32_f16 v[54:57], v[74:77], v[58:61], v[54:57]
	ds_read_b128 v[58:61], v5
	v_mfma_f32_16x16x32_f16 v[54:57], v[78:81], v[66:69], v[54:57]
	ds_read_b128 v[62:65], v5 offset:64
	ds_read_b128 v[66:69], v2
	ds_read_b128 v[70:73], v2 offset:64
	s_waitcnt lgkmcnt(1)
	v_mfma_f32_16x16x32_f16 v[54:57], v[58:61], v[66:69], v[54:57]
	ds_read_b128 v[58:61], v5 offset:128
	ds_read_b128 v[66:69], v5 offset:192
	s_waitcnt lgkmcnt(2)
	v_mfma_f32_16x16x32_f16 v[54:57], v[62:65], v[70:73], v[54:57]
	ds_read_b128 v[62:65], v2 offset:128
	ds_read_b128 v[70:73], v2 offset:192
	s_waitcnt lgkmcnt(1)
	v_mfma_f32_16x16x32_f16 v[54:57], v[58:61], v[62:65], v[54:57]
	ds_read_b128 v[58:61], v5 offset:256
	ds_read_b128 v[62:65], v5 offset:320
	s_waitcnt lgkmcnt(2)
	v_mfma_f32_16x16x32_f16 v[54:57], v[66:69], v[70:73], v[54:57]
	ds_read_b128 v[66:69], v2 offset:256
	ds_read_b128 v[70:73], v2 offset:320
	ds_read_b128 v[74:77], v5 offset:384
	s_waitcnt lgkmcnt(2)
	v_mfma_f32_16x16x32_f16 v[54:57], v[58:61], v[66:69], v[54:57]
	ds_read_b128 v[58:61], v2 offset:384
	ds_read_b128 v[66:69], v2 offset:448
	ds_read_b128 v[78:81], v5 offset:448
	s_waitcnt lgkmcnt(0)
	s_barrier
	s_waitcnt vmcnt(17)
	ds_write_b128 v4, v[178:181]
	s_waitcnt vmcnt(16)
	ds_write_b128 v6, v[182:185]
	s_waitcnt vmcnt(15)
	ds_write_b128 v8, v[186:189]
	s_waitcnt vmcnt(14)
	ds_write_b128 v10, v[190:193]
	s_waitcnt vmcnt(13)
	ds_write_b128 v12, v[194:197]
	s_waitcnt vmcnt(12)
	ds_write_b128 v14, v[198:201]
	s_waitcnt lgkmcnt(0)
	s_barrier
	global_load_dwordx4 v[178:181], v[18:19], off offset:3584
	global_load_dwordx4 v[182:185], v[16:17], off offset:3584
	global_load_dwordx4 v[186:189], v[20:21], off offset:3584
	global_load_dwordx4 v[190:193], v[22:23], off offset:3584
	global_load_dwordx4 v[194:197], v[24:25], off offset:3584
	global_load_dwordx4 v[198:201], v[26:27], off offset:3584
	v_mfma_f32_16x16x32_f16 v[54:57], v[62:65], v[70:73], v[54:57]
	v_mfma_f32_16x16x32_f16 v[54:57], v[74:77], v[58:61], v[54:57]
	ds_read_b128 v[58:61], v5
	v_mfma_f32_16x16x32_f16 v[54:57], v[78:81], v[66:69], v[54:57]
	ds_read_b128 v[62:65], v5 offset:64
	ds_read_b128 v[66:69], v2
	ds_read_b128 v[70:73], v2 offset:64
	s_waitcnt lgkmcnt(1)
	v_mfma_f32_16x16x32_f16 v[54:57], v[58:61], v[66:69], v[54:57]
	ds_read_b128 v[58:61], v5 offset:128
	ds_read_b128 v[66:69], v5 offset:192
	s_waitcnt lgkmcnt(2)
	v_mfma_f32_16x16x32_f16 v[54:57], v[62:65], v[70:73], v[54:57]
	ds_read_b128 v[62:65], v2 offset:128
	ds_read_b128 v[70:73], v2 offset:192
	s_waitcnt lgkmcnt(1)
	v_mfma_f32_16x16x32_f16 v[54:57], v[58:61], v[62:65], v[54:57]
	ds_read_b128 v[58:61], v5 offset:256
	ds_read_b128 v[62:65], v5 offset:320
	s_waitcnt lgkmcnt(2)
	v_mfma_f32_16x16x32_f16 v[54:57], v[66:69], v[70:73], v[54:57]
	ds_read_b128 v[66:69], v2 offset:256
	ds_read_b128 v[70:73], v2 offset:320
	ds_read_b128 v[74:77], v5 offset:384
	s_waitcnt lgkmcnt(2)
	v_mfma_f32_16x16x32_f16 v[54:57], v[58:61], v[66:69], v[54:57]
	ds_read_b128 v[58:61], v2 offset:384
	ds_read_b128 v[66:69], v2 offset:448
	ds_read_b128 v[78:81], v5 offset:448
	s_waitcnt lgkmcnt(0)
	s_barrier
	s_waitcnt vmcnt(17)
	ds_write_b128 v4, v[206:209]
	s_waitcnt vmcnt(16)
	ds_write_b128 v6, v[210:213]
	s_waitcnt vmcnt(15)
	ds_write_b128 v8, v[214:217]
	s_waitcnt vmcnt(14)
	ds_write_b128 v10, v[218:221]
	s_waitcnt vmcnt(13)
	ds_write_b128 v12, v[120:123]
	s_waitcnt vmcnt(12)
	ds_write_b128 v14, v[124:127]
	s_waitcnt lgkmcnt(0)
	s_barrier
	global_load_dwordx4 v[206:209], v[128:129], off
	global_load_dwordx4 v[210:213], v[130:131], off
	global_load_dwordx4 v[214:217], v[132:133], off
	global_load_dwordx4 v[218:221], v[106:107], off
	global_load_dwordx4 v[120:123], v[108:109], off
	global_load_dwordx4 v[124:127], v[110:111], off
	v_mfma_f32_16x16x32_f16 v[54:57], v[62:65], v[70:73], v[54:57]
	v_mfma_f32_16x16x32_f16 v[54:57], v[74:77], v[58:61], v[54:57]
	ds_read_b128 v[58:61], v5
	v_mfma_f32_16x16x32_f16 v[54:57], v[78:81], v[66:69], v[54:57]
	ds_read_b128 v[62:65], v2
	ds_read_b128 v[66:69], v2 offset:64
	ds_read_b128 v[70:73], v5 offset:64
	ds_read_b128 v[74:77], v2 offset:128
	ds_read_b128 v[78:81], v2 offset:192
	ds_read_b128 v[82:85], v5 offset:128
	ds_read_b128 v[86:89], v5 offset:192
	s_waitcnt lgkmcnt(6)
	v_mfma_f32_16x16x32_f16 v[54:57], v[58:61], v[62:65], v[54:57]
	ds_read_b128 v[58:61], v2 offset:256
	ds_read_b128 v[62:65], v2 offset:320
	ds_read_b128 v[90:93], v5 offset:256
	ds_read_b128 v[94:97], v5 offset:320
	s_waitcnt lgkmcnt(8)
	v_mfma_f32_16x16x32_f16 v[54:57], v[70:73], v[66:69], v[54:57]
	ds_read_b128 v[66:69], v2 offset:384
	ds_read_b128 v[70:73], v2 offset:448
	ds_read_b128 v[98:101], v5 offset:384
	ds_read_b128 v[102:105], v5 offset:448
	s_waitcnt lgkmcnt(0)
	s_barrier
	s_waitcnt vmcnt(17)
	ds_write_b128 v4, v[136:139]
	s_waitcnt vmcnt(16)
	ds_write_b128 v6, v[140:143]
	s_waitcnt vmcnt(15)
	ds_write_b128 v8, v[144:147]
	s_waitcnt vmcnt(14)
	ds_write_b128 v10, v[148:151]
	s_waitcnt vmcnt(13)
	ds_write_b128 v12, v[152:155]
	s_waitcnt vmcnt(12)
	ds_write_b128 v14, v[156:159]
	s_waitcnt lgkmcnt(0)
	s_barrier
	global_load_dwordx4 v[136:139], v[128:129], off offset:512
	global_load_dwordx4 v[140:143], v[130:131], off offset:512
	global_load_dwordx4 v[144:147], v[132:133], off offset:512
	global_load_dwordx4 v[148:151], v[106:107], off offset:512
	global_load_dwordx4 v[152:155], v[108:109], off offset:512
	global_load_dwordx4 v[156:159], v[110:111], off offset:512
	v_mfma_f32_16x16x32_f16 v[54:57], v[82:85], v[74:77], v[54:57]
	v_mfma_f32_16x16x32_f16 v[54:57], v[86:89], v[78:81], v[54:57]
	v_add_co_u32_e32 v78, vcc, s24, v18
	v_mfma_f32_16x16x32_f16 v[54:57], v[90:93], v[58:61], v[54:57]
	s_nop 0
	v_addc_co_u32_e32 v79, vcc, 0, v19, vcc
	v_add_co_u32_e32 v80, vcc, s24, v26
	v_mfma_f32_16x16x32_f16 v[54:57], v[94:97], v[62:65], v[54:57]
	s_nop 0
	v_addc_co_u32_e32 v81, vcc, 0, v27, vcc
	v_add_co_u32_e32 v82, vcc, s24, v24
	v_mfma_f32_16x16x32_f16 v[54:57], v[98:101], v[66:69], v[54:57]
	s_nop 0
	v_addc_co_u32_e32 v83, vcc, 0, v25, vcc
	ds_read_b128 v[24:27], v5
	v_mfma_f32_16x16x32_f16 v[54:57], v[102:105], v[70:73], v[54:57]
	ds_read_b128 v[58:61], v2
	ds_read_b128 v[62:65], v5 offset:64
	v_add_co_u32_e32 v84, vcc, s24, v22
	ds_read_b128 v[66:69], v2 offset:64
	s_nop 0
	v_addc_co_u32_e32 v85, vcc, 0, v23, vcc
	s_waitcnt lgkmcnt(2)
	v_mfma_f32_16x16x32_f16 v[22:25], v[24:27], v[58:61], v[54:57]
	s_nop 2
	ds_read_b128 v[54:57], v5 offset:128
	ds_read_b128 v[58:61], v2 offset:128
	ds_read_b128 v[70:73], v5 offset:192
	v_add_co_u32_e32 v86, vcc, s24, v20
	s_waitcnt lgkmcnt(3)
	v_mfma_f32_16x16x32_f16 v[22:25], v[62:65], v[66:69], v[22:25]
	v_addc_co_u32_e32 v87, vcc, 0, v21, vcc
	ds_read_b128 v[18:21], v2 offset:192
	s_waitcnt lgkmcnt(2)
	v_mfma_f32_16x16x32_f16 v[22:25], v[54:57], v[58:61], v[22:25]
	ds_read_b128 v[54:57], v2 offset:256
	ds_read_b128 v[58:61], v5 offset:256
	ds_read_b128 v[62:65], v5 offset:320
	v_add_co_u32_e32 v88, vcc, s24, v16
	s_waitcnt lgkmcnt(3)
	v_mfma_f32_16x16x32_f16 v[18:21], v[70:73], v[18:21], v[22:25]
	v_addc_co_u32_e32 v89, vcc, 0, v17, vcc
	s_nop 1
	ds_read_b128 v[22:25], v2 offset:320
	ds_read_b128 v[66:69], v5 offset:384
	s_waitcnt lgkmcnt(3)
	v_mfma_f32_16x16x32_f16 v[16:19], v[58:61], v[54:57], v[18:21]
	ds_read_b128 v[54:57], v2 offset:384
	ds_read_b128 v[58:61], v2 offset:448
	ds_read_b128 v[70:73], v5 offset:448
	s_waitcnt lgkmcnt(0)
	s_barrier
	v_mfma_f32_16x16x32_f16 v[16:19], v[62:65], v[22:25], v[16:19]
	s_waitcnt vmcnt(17)
	ds_write_b128 v4, v[178:181]
	s_waitcnt vmcnt(16)
	ds_write_b128 v6, v[182:185]
	s_waitcnt vmcnt(15)
	ds_write_b128 v8, v[186:189]
	s_waitcnt vmcnt(14)
	ds_write_b128 v10, v[190:193]
	s_waitcnt vmcnt(13)
	ds_write_b128 v12, v[194:197]
	s_waitcnt vmcnt(12)
	ds_write_b128 v14, v[198:201]
	s_waitcnt lgkmcnt(0)
	s_barrier
	global_load_dwordx4 v[178:181], v[128:129], off offset:1024
	global_load_dwordx4 v[182:185], v[130:131], off offset:1024
	global_load_dwordx4 v[186:189], v[132:133], off offset:1024
	global_load_dwordx4 v[190:193], v[106:107], off offset:1024
	global_load_dwordx4 v[194:197], v[108:109], off offset:1024
	global_load_dwordx4 v[198:201], v[110:111], off offset:1024
	ds_read_b128 v[46:49], v5
	v_mfma_f32_16x16x32_f16 v[16:19], v[66:69], v[54:57], v[16:19]
	v_cmp_gt_u32_e32 vcc, 16, v28
	v_mfma_f32_16x16x32_f16 v[16:19], v[70:73], v[58:61], v[16:19]
	ds_read_b128 v[50:53], v5 offset:64
	ds_read_b128 v[54:57], v2
	ds_read_b128 v[58:61], v2 offset:64
	s_waitcnt lgkmcnt(1)
	v_mfma_f32_16x16x32_f16 v[16:19], v[46:49], v[54:57], v[16:19]
	ds_read_b128 v[46:49], v5 offset:128
	ds_read_b128 v[54:57], v5 offset:192
	s_waitcnt lgkmcnt(2)
	v_mfma_f32_16x16x32_f16 v[16:19], v[50:53], v[58:61], v[16:19]
	ds_read_b128 v[50:53], v2 offset:128
	ds_read_b128 v[58:61], v2 offset:192
	s_waitcnt lgkmcnt(1)
	v_mfma_f32_16x16x32_f16 v[16:19], v[46:49], v[50:53], v[16:19]
	ds_read_b128 v[46:49], v5 offset:256
	ds_read_b128 v[50:53], v5 offset:320
	s_waitcnt lgkmcnt(2)
	v_mfma_f32_16x16x32_f16 v[16:19], v[54:57], v[58:61], v[16:19]
	ds_read_b128 v[54:57], v2 offset:256
	ds_read_b128 v[58:61], v2 offset:320
	ds_read_b128 v[62:65], v5 offset:384
	s_waitcnt lgkmcnt(2)
	v_mfma_f32_16x16x32_f16 v[16:19], v[46:49], v[54:57], v[16:19]
	ds_read_b128 v[46:49], v2 offset:384
	ds_read_b128 v[54:57], v2 offset:448
	ds_read_b128 v[66:69], v5 offset:448
	s_waitcnt lgkmcnt(0)
	s_barrier
	s_waitcnt vmcnt(17)
	ds_write_b128 v4, v[206:209]
	s_waitcnt vmcnt(16)
	ds_write_b128 v6, v[210:213]
	s_waitcnt vmcnt(15)
	ds_write_b128 v8, v[214:217]
	s_waitcnt vmcnt(14)
	ds_write_b128 v10, v[218:221]
	s_waitcnt vmcnt(13)
	ds_write_b128 v12, v[120:123]
	s_waitcnt vmcnt(12)
	ds_write_b128 v14, v[124:127]
	s_waitcnt lgkmcnt(0)
	s_barrier
	v_mfma_f32_16x16x32_f16 v[16:19], v[50:53], v[58:61], v[16:19]
	v_mfma_f32_16x16x32_f16 v[16:19], v[62:65], v[46:49], v[16:19]
	ds_read_b128 v[46:49], v5
	v_mfma_f32_16x16x32_f16 v[16:19], v[66:69], v[54:57], v[16:19]
	ds_read_b128 v[50:53], v5 offset:64
	ds_read_b128 v[54:57], v2
	ds_read_b128 v[58:61], v2 offset:64
	s_waitcnt lgkmcnt(1)
	v_mfma_f32_16x16x32_f16 v[16:19], v[46:49], v[54:57], v[16:19]
	ds_read_b128 v[46:49], v5 offset:128
	ds_read_b128 v[54:57], v5 offset:192
	s_waitcnt lgkmcnt(2)
	v_mfma_f32_16x16x32_f16 v[16:19], v[50:53], v[58:61], v[16:19]
	ds_read_b128 v[50:53], v2 offset:128
	ds_read_b128 v[58:61], v2 offset:192
	ds_read_b128 v[62:65], v5 offset:256
	s_waitcnt lgkmcnt(2)
	v_mfma_f32_16x16x32_f16 v[16:19], v[46:49], v[50:53], v[16:19]
	ds_read_b128 v[46:49], v2 offset:256
	ds_read_b128 v[50:53], v2 offset:320
	ds_read_b128 v[66:69], v5 offset:320
	s_waitcnt lgkmcnt(4)
	v_mfma_f32_16x16x32_f16 v[16:19], v[54:57], v[58:61], v[16:19]
	ds_read_b128 v[54:57], v2 offset:384
	ds_read_b128 v[58:61], v2 offset:448
	ds_read_b128 v[70:73], v5 offset:384
	ds_read_b128 v[74:77], v5 offset:448
	s_waitcnt lgkmcnt(0)
	s_barrier
	s_waitcnt vmcnt(11)
	ds_write_b128 v4, v[136:139]
	s_waitcnt vmcnt(10)
	ds_write_b128 v6, v[140:143]
	s_waitcnt vmcnt(9)
	ds_write_b128 v8, v[144:147]
	s_waitcnt vmcnt(8)
	ds_write_b128 v10, v[148:151]
	s_waitcnt vmcnt(7)
	ds_write_b128 v12, v[152:155]
	s_waitcnt vmcnt(6)
	ds_write_b128 v14, v[156:159]
	s_waitcnt lgkmcnt(0)
	s_barrier
	v_mfma_f32_16x16x32_f16 v[16:19], v[62:65], v[46:49], v[16:19]
	ds_read_b128 v[46:49], v5
	v_mfma_f32_16x16x32_f16 v[16:19], v[66:69], v[50:53], v[16:19]
	v_mfma_f32_16x16x32_f16 v[16:19], v[70:73], v[54:57], v[16:19]
	ds_read_b128 v[50:53], v2
	ds_read_b128 v[54:57], v5 offset:64
	v_mfma_f32_16x16x32_f16 v[16:19], v[74:77], v[58:61], v[16:19]
	ds_read_b128 v[58:61], v2 offset:64
	ds_read_b128 v[62:65], v5 offset:128
	s_waitcnt lgkmcnt(3)
	v_mfma_f32_16x16x32_f16 v[16:19], v[46:49], v[50:53], v[16:19]
	ds_read_b128 v[46:49], v2 offset:128
	ds_read_b128 v[50:53], v5 offset:192
	s_waitcnt lgkmcnt(3)
	v_mfma_f32_16x16x32_f16 v[16:19], v[54:57], v[58:61], v[16:19]
	ds_read_b128 v[54:57], v2 offset:192
	ds_read_b128 v[58:61], v5 offset:256
	s_waitcnt lgkmcnt(3)
	v_mfma_f32_16x16x32_f16 v[16:19], v[62:65], v[46:49], v[16:19]
	ds_read_b128 v[46:49], v2 offset:256
	ds_read_b128 v[62:65], v2 offset:320
	ds_read_b128 v[66:69], v5 offset:320
	s_waitcnt lgkmcnt(4)
	v_mfma_f32_16x16x32_f16 v[16:19], v[50:53], v[54:57], v[16:19]
	ds_read_b128 v[50:53], v2 offset:384
	ds_read_b128 v[54:57], v2 offset:448
	ds_read_b128 v[70:73], v5 offset:384
	ds_read_b128 v[74:77], v5 offset:448
	s_waitcnt lgkmcnt(0)
	s_barrier
	v_mfma_f32_16x16x32_f16 v[16:19], v[58:61], v[46:49], v[16:19]
	s_waitcnt vmcnt(5)
	ds_write_b128 v4, v[178:181]
	s_waitcnt vmcnt(4)
	ds_write_b128 v6, v[182:185]
	s_waitcnt vmcnt(3)
	ds_write_b128 v8, v[186:189]
	s_waitcnt vmcnt(2)
	ds_write_b128 v10, v[190:193]
	s_waitcnt vmcnt(1)
	ds_write_b128 v12, v[194:197]
	s_waitcnt vmcnt(0)
	ds_write_b128 v14, v[198:201]
	v_mfma_f32_16x16x32_f16 v[16:19], v[66:69], v[62:65], v[16:19]
	s_waitcnt lgkmcnt(0)
	s_barrier
	ds_read_b128 v[6:9], v5
	v_mfma_f32_16x16x32_f16 v[10:13], v[70:73], v[50:53], v[16:19]
	s_nop 3
	ds_read_b128 v[14:17], v2
	ds_read_b128 v[18:21], v5 offset:64
	ds_read_b128 v[22:25], v2 offset:64
	ds_read_b128 v[30:33], v5 offset:128
	v_add_u32_e32 v26, s15, v3
	v_mfma_f32_16x16x32_f16 v[10:13], v[74:77], v[54:57], v[10:13]
	v_lshlrev_b64 v[34:35], 10, v[0:1]
	v_ashrrev_i32_e32 v27, 31, v26
	v_lshl_add_u64 v[34:35], v[34:35], 0, v[26:27]
	s_waitcnt lgkmcnt(3)
	v_mfma_f32_16x16x32_f16 v[6:9], v[6:9], v[14:17], v[10:13]
	s_nop 2
	ds_read_b128 v[10:13], v2 offset:128
	ds_read_b128 v[14:17], v5 offset:192
	v_lshlrev_b64 v[26:27], 2, v[26:27]
	v_lshl_add_u64 v[36:37], v[34:35], 2, s[38:39]
	s_waitcnt lgkmcnt(3)
	v_mfma_f32_16x16x32_f16 v[6:9], v[18:21], v[22:25], v[6:9]
	ds_read_b128 v[18:21], v2 offset:192
	ds_read_b128 v[22:25], v5 offset:256
	s_waitcnt lgkmcnt(3)
	v_mfma_f32_16x16x32_f16 v[6:9], v[30:33], v[10:13], v[6:9]
	ds_read_b128 v[10:13], v2 offset:256
	ds_read_b128 v[30:33], v5 offset:320
	s_waitcnt lgkmcnt(3)
	v_mfma_f32_16x16x32_f16 v[6:9], v[14:17], v[18:21], v[6:9]
	ds_read_b128 v[14:17], v2 offset:320
	ds_read_b128 v[18:21], v5 offset:384
	s_waitcnt lgkmcnt(3)
	v_mfma_f32_16x16x32_f16 v[6:9], v[22:25], v[10:13], v[6:9]
	ds_read_b128 v[10:13], v2 offset:384
	v_lshl_add_u64 v[22:23], s[2:3], 0, v[26:27]
	s_waitcnt lgkmcnt(2)
	v_mfma_f32_16x16x32_f16 v[6:9], v[30:33], v[14:17], v[6:9]
	ds_read_b128 v[14:17], v2 offset:448
	ds_read_b128 v[2:5], v5 offset:448
	global_load_dwordx4 v[22:25], v[22:23], off
	s_waitcnt lgkmcnt(2)
	v_mfma_f32_16x16x32_f16 v[6:9], v[18:21], v[10:13], v[6:9]
	global_load_dwordx4 v[10:13], v[36:37], off
	v_lshl_add_u64 v[18:19], s[4:5], 0, v[26:27]
	s_waitcnt lgkmcnt(0)
	v_mfma_f32_16x16x32_f16 v[2:5], v[2:5], v[14:17], v[6:9]
	s_waitcnt vmcnt(1)
	s_nop 2
	v_pk_mul_f32 v[6:7], v[24:25], 0.5 op_sel_hi:[1,0]
	v_pk_mul_f32 v[8:9], v[22:23], 0.5 op_sel_hi:[1,0]
	s_waitcnt vmcnt(0)
	s_nop 0
	v_pk_fma_f32 v[6:7], v[4:5], v[6:7], v[12:13]
	v_pk_fma_f32 v[4:5], v[2:3], v[8:9], v[10:11]
	global_store_dwordx4 v[36:37], v[4:7], off
	global_load_dwordx4 v[8:11], v[18:19], off
	v_mul_f32_e32 v2, v5, v5
	v_mul_f32_e32 v3, v7, v7
	v_fmac_f32_e32 v2, v4, v4
	v_fmac_f32_e32 v3, v6, v6
	v_add_f32_e32 v2, v2, v3
	ds_bpermute_b32 v3, v134, v2
	v_lshl_add_u64 v[12:13], v[34:35], 1, s[42:43]
	s_waitcnt lgkmcnt(0)
	v_add_f32_e32 v2, v2, v3
	ds_bpermute_b32 v3, v135, v2
	s_waitcnt vmcnt(0)
	v_pk_mul_f32 v[6:7], v[10:11], v[6:7]
	v_pk_mul_f32 v[4:5], v[8:9], v[4:5]
	s_nop 0
	v_cvt_pk_f16_f32 v4, v4, v5
	v_cvt_pk_f16_f32 v5, v6, v7
	global_store_dwordx2 v[12:13], v[4:5], off
	s_and_saveexec_b64 s[14:15], vcc
	s_cbranch_execz .LBB0_364
	v_lshlrev_b32_e32 v0, 2, v0
	s_waitcnt lgkmcnt(0)
	v_add_f32_e32 v2, v2, v3
	global_atomic_add_f32 v0, v2, s[12:13]
	s_branch .LBB0_364

.LBB0_1244:
	v_mov_b32_e32 v28, v176
	s_and_b32 s4, s20, 0x1e0
	v_add_u32_e32 v8, s14, v28
	s_and_b32 s5, s18, 0xffffffc0
	s_bitset1_b32 s4, 14
	s_sub_i32 s26, s5, 32
	v_lshlrev_b32_e32 v0, 4, v28
	v_ashrrev_i32_e32 v9, 5, v8
	v_and_b32_e32 v0, 0x1f0, v0
	v_mov_b32_e32 v10, s26
	v_mov_b32_e32 v11, s4
	v_cmp_gt_i32_e32 vcc, 32, v9
	v_lshl_add_u64 v[2:3], s[10:11], 0, v[0:1]
	v_lshl_add_u64 v[4:5], s[36:37], 0, v[0:1]
	v_cndmask_b32_e32 v6, v10, v11, vcc
	v_add_u32_e32 v12, v6, v9
	v_cndmask_b32_e32 v7, v3, v5, vcc
	v_cndmask_b32_e32 v6, v2, v4, vcc
	v_mad_i64_i32 v[18:19], s[26:27], v12, s22, v[6:7]
	v_add_u32_e32 v6, 0x200, v8
	v_ashrrev_i32_e32 v12, 5, v6
	v_cmp_gt_i32_e32 vcc, 32, v12
	v_add_u32_e32 v0, 0, v0
	s_or_b32 s5, s5, s16
	v_cndmask_b32_e32 v6, v10, v11, vcc
	v_add_u32_e32 v13, v6, v12
	v_cndmask_b32_e32 v7, v3, v5, vcc
	v_cndmask_b32_e32 v6, v2, v4, vcc
	v_mad_i64_i32 v[16:17], s[26:27], v13, s22, v[6:7]
	v_add_u32_e32 v6, 0x400, v8
	v_ashrrev_i32_e32 v13, 5, v6
	v_cmp_gt_i32_e32 vcc, 32, v13
	s_add_i32 s4, s4, s15
	s_nop 0
	v_cndmask_b32_e32 v6, v10, v11, vcc
	v_add_u32_e32 v14, v6, v13
	v_cndmask_b32_e32 v7, v3, v5, vcc
	v_cndmask_b32_e32 v6, v2, v4, vcc
	v_mad_i64_i32 v[20:21], s[26:27], v14, s22, v[6:7]
	v_add_u32_e32 v6, 0x600, v8
	v_ashrrev_i32_e32 v14, 5, v6
	v_cmp_gt_i32_e32 vcc, 32, v14
	s_nop 1
	v_cndmask_b32_e32 v6, v10, v11, vcc
	v_add_u32_e32 v15, v6, v14
	v_cndmask_b32_e32 v7, v3, v5, vcc
	v_cndmask_b32_e32 v6, v2, v4, vcc
	v_mad_i64_i32 v[22:23], s[26:27], v15, s22, v[6:7]
	v_add_u32_e32 v6, 0x800, v8
	v_ashrrev_i32_e32 v15, 5, v6
	v_cmp_gt_i32_e32 vcc, 32, v15
	s_nop 1
	v_cndmask_b32_e32 v6, v10, v11, vcc
	v_add_u32_e32 v24, v6, v15
	v_cndmask_b32_e32 v7, v3, v5, vcc
	v_cndmask_b32_e32 v6, v2, v4, vcc
	v_mad_i64_i32 v[24:25], s[26:27], v24, s22, v[6:7]
	v_add_u32_e32 v6, 0xa00, v8
	v_ashrrev_i32_e32 v29, 5, v6
	v_cmp_gt_i32_e32 vcc, 32, v29
	s_nop 1
	v_cndmask_b32_e32 v6, v10, v11, vcc
	v_add_u32_e32 v6, v6, v29
	v_cndmask_b32_e32 v3, v3, v5, vcc
	v_cndmask_b32_e32 v2, v2, v4, vcc
	v_mad_i64_i32 v[26:27], s[26:27], v6, s22, v[2:3]
	global_load_dwordx4 v[136:139], v[18:19], off
	global_load_dwordx4 v[140:143], v[16:17], off
	global_load_dwordx4 v[144:147], v[20:21], off
	global_load_dwordx4 v[148:151], v[22:23], off
	global_load_dwordx4 v[152:155], v[24:25], off
	global_load_dwordx4 v[156:159], v[26:27], off
	global_load_dwordx4 v[178:181], v[18:19], off offset:512
	global_load_dwordx4 v[182:185], v[16:17], off offset:512
	global_load_dwordx4 v[186:189], v[20:21], off offset:512
	global_load_dwordx4 v[190:193], v[22:23], off offset:512
	global_load_dwordx4 v[194:197], v[24:25], off offset:512
	global_load_dwordx4 v[198:201], v[26:27], off offset:512
	global_load_dwordx4 v[206:209], v[18:19], off offset:1024
	global_load_dwordx4 v[210:213], v[16:17], off offset:1024
	global_load_dwordx4 v[214:217], v[20:21], off offset:1024
	global_load_dwordx4 v[218:221], v[22:23], off offset:1024
	global_load_dwordx4 v[120:123], v[24:25], off offset:1024
	global_load_dwordx4 v[124:127], v[26:27], off offset:1024
	v_mov_b32_e32 v112, 0x1000
	v_mov_b32_e32 v113, 0
	v_lshl_add_u64 v[128:129], v[18:19], 0, v[112:113]
	v_lshl_add_u64 v[130:131], v[16:17], 0, v[112:113]
	v_lshl_add_u64 v[132:133], v[20:21], 0, v[112:113]
	v_lshl_add_u64 v[106:107], v[22:23], 0, v[112:113]
	v_lshl_add_u64 v[108:109], v[24:25], 0, v[112:113]
	v_lshl_add_u64 v[110:111], v[26:27], 0, v[112:113]
	v_mad_u64_u32 v[4:5], s[26:27], v9, s23, v[0:1]
	v_mad_u64_u32 v[6:7], s[26:27], v12, s23, v[0:1]
	v_mad_u64_u32 v[8:9], s[26:27], v13, s23, v[0:1]
	v_mad_u64_u32 v[10:11], s[26:27], v14, s23, v[0:1]
	v_mad_u64_u32 v[12:13], s[26:27], v15, s23, v[0:1]
	v_mad_u64_u32 v[14:15], s[26:27], v29, s23, v[0:1]
	s_barrier
	v_and_b32_e32 v0, 15, v28
	v_and_b32_e32 v2, -16, v28
	v_add_u32_e32 v2, 0, v2
	v_or_b32_e32 v5, s17, v0
	v_mad_u32_u24 v5, v5, s23, v2
	v_or_b32_e32 v3, s15, v0
	v_mad_u64_u32 v[2:3], s[26:27], v3, s23, v[2:3]
	v_ashrrev_i32_e32 v3, 2, v28
	v_and_b32_e32 v3, -4, v3
	v_or_b32_e32 v0, s4, v0
	s_waitcnt vmcnt(17)
	ds_write_b128 v4, v[136:139]
	s_waitcnt vmcnt(16)
	ds_write_b128 v6, v[140:143]
	s_waitcnt vmcnt(15)
	ds_write_b128 v8, v[144:147]
	s_waitcnt vmcnt(14)
	ds_write_b128 v10, v[148:151]
	s_waitcnt vmcnt(13)
	ds_write_b128 v12, v[152:155]
	s_waitcnt vmcnt(12)
	ds_write_b128 v14, v[156:159]
	s_waitcnt lgkmcnt(0)
	s_barrier
	global_load_dwordx4 v[136:139], v[18:19], off offset:1536
	global_load_dwordx4 v[140:143], v[16:17], off offset:1536
	global_load_dwordx4 v[144:147], v[20:21], off offset:1536
	global_load_dwordx4 v[148:151], v[22:23], off offset:1536
	global_load_dwordx4 v[152:155], v[24:25], off offset:1536
	global_load_dwordx4 v[156:159], v[26:27], off offset:1536
	ds_read_b128 v[54:57], v5
	ds_read_b128 v[58:61], v5 offset:64
	ds_read_b128 v[62:65], v2
	ds_read_b128 v[66:69], v2 offset:64
	s_waitcnt lgkmcnt(1)
	v_mfma_f32_16x16x32_f16 v[54:57], v[54:57], v[62:65], 0
	ds_read_b128 v[62:65], v5 offset:128
	ds_read_b128 v[70:73], v5 offset:192
	s_waitcnt lgkmcnt(2)
	v_mfma_f32_16x16x32_f16 v[54:57], v[58:61], v[66:69], v[54:57]
	ds_read_b128 v[58:61], v2 offset:128
	ds_read_b128 v[66:69], v2 offset:192
	s_waitcnt lgkmcnt(1)
	v_mfma_f32_16x16x32_f16 v[54:57], v[62:65], v[58:61], v[54:57]
	ds_read_b128 v[58:61], v5 offset:256
	ds_read_b128 v[62:65], v5 offset:320
	s_waitcnt lgkmcnt(2)
	v_mfma_f32_16x16x32_f16 v[54:57], v[70:73], v[66:69], v[54:57]
	ds_read_b128 v[66:69], v2 offset:256
	ds_read_b128 v[70:73], v2 offset:320
	ds_read_b128 v[74:77], v5 offset:384
	s_waitcnt lgkmcnt(2)
	v_mfma_f32_16x16x32_f16 v[54:57], v[58:61], v[66:69], v[54:57]
	ds_read_b128 v[58:61], v2 offset:384
	ds_read_b128 v[66:69], v2 offset:448
	ds_read_b128 v[78:81], v5 offset:448
	s_waitcnt lgkmcnt(0)
	s_barrier
	s_waitcnt vmcnt(17)
	ds_write_b128 v4, v[178:181]
	s_waitcnt vmcnt(16)
	ds_write_b128 v6, v[182:185]
	s_waitcnt vmcnt(15)
	ds_write_b128 v8, v[186:189]
	s_waitcnt vmcnt(14)
	ds_write_b128 v10, v[190:193]
	s_waitcnt vmcnt(13)
	ds_write_b128 v12, v[194:197]
	s_waitcnt vmcnt(12)
	ds_write_b128 v14, v[198:201]
	s_waitcnt lgkmcnt(0)
	s_barrier
	global_load_dwordx4 v[178:181], v[18:19], off offset:2048
	global_load_dwordx4 v[182:185], v[16:17], off offset:2048
	global_load_dwordx4 v[186:189], v[20:21], off offset:2048
	global_load_dwordx4 v[190:193], v[22:23], off offset:2048
	global_load_dwordx4 v[194:197], v[24:25], off offset:2048
	global_load_dwordx4 v[198:201], v[26:27], off offset:2048
	v_mfma_f32_16x16x32_f16 v[54:57], v[62:65], v[70:73], v[54:57]
	v_mfma_f32_16x16x32_f16 v[54:57], v[74:77], v[58:61], v[54:57]
	ds_read_b128 v[58:61], v5
	v_mfma_f32_16x16x32_f16 v[54:57], v[78:81], v[66:69], v[54:57]
	ds_read_b128 v[62:65], v5 offset:64
	ds_read_b128 v[66:69], v2
	ds_read_b128 v[70:73], v2 offset:64
	s_waitcnt lgkmcnt(1)
	v_mfma_f32_16x16x32_f16 v[54:57], v[58:61], v[66:69], v[54:57]
	ds_read_b128 v[58:61], v5 offset:128
	ds_read_b128 v[66:69], v5 offset:192
	s_waitcnt lgkmcnt(2)
	v_mfma_f32_16x16x32_f16 v[54:57], v[62:65], v[70:73], v[54:57]
	ds_read_b128 v[62:65], v2 offset:128
	ds_read_b128 v[70:73], v2 offset:192
	s_waitcnt lgkmcnt(1)
	v_mfma_f32_16x16x32_f16 v[54:57], v[58:61], v[62:65], v[54:57]
	ds_read_b128 v[58:61], v5 offset:256
	ds_read_b128 v[62:65], v5 offset:320
	s_waitcnt lgkmcnt(2)
	v_mfma_f32_16x16x32_f16 v[54:57], v[66:69], v[70:73], v[54:57]
	ds_read_b128 v[66:69], v2 offset:256
	ds_read_b128 v[70:73], v2 offset:320
	ds_read_b128 v[74:77], v5 offset:384
	s_waitcnt lgkmcnt(2)
	v_mfma_f32_16x16x32_f16 v[54:57], v[58:61], v[66:69], v[54:57]
	ds_read_b128 v[58:61], v2 offset:384
	ds_read_b128 v[66:69], v2 offset:448
	ds_read_b128 v[78:81], v5 offset:448
	s_waitcnt lgkmcnt(0)
	s_barrier
	s_waitcnt vmcnt(17)
	ds_write_b128 v4, v[206:209]
	s_waitcnt vmcnt(16)
	ds_write_b128 v6, v[210:213]
	s_waitcnt vmcnt(15)
	ds_write_b128 v8, v[214:217]
	s_waitcnt vmcnt(14)
	ds_write_b128 v10, v[218:221]
	s_waitcnt vmcnt(13)
	ds_write_b128 v12, v[120:123]
	s_waitcnt vmcnt(12)
	ds_write_b128 v14, v[124:127]
	s_waitcnt lgkmcnt(0)
	s_barrier
	global_load_dwordx4 v[206:209], v[18:19], off offset:2560
	global_load_dwordx4 v[210:213], v[16:17], off offset:2560
	global_load_dwordx4 v[214:217], v[20:21], off offset:2560
	global_load_dwordx4 v[218:221], v[22:23], off offset:2560
	global_load_dwordx4 v[120:123], v[24:25], off offset:2560
	global_load_dwordx4 v[124:127], v[26:27], off offset:2560
	v_mfma_f32_16x16x32_f16 v[54:57], v[62:65], v[70:73], v[54:57]
	v_mfma_f32_16x16x32_f16 v[54:57], v[74:77], v[58:61], v[54:57]
	ds_read_b128 v[58:61], v5
	v_mfma_f32_16x16x32_f16 v[54:57], v[78:81], v[66:69], v[54:57]
	ds_read_b128 v[62:65], v5 offset:64
	ds_read_b128 v[66:69], v2
	ds_read_b128 v[70:73], v2 offset:64
	s_waitcnt lgkmcnt(1)
	v_mfma_f32_16x16x32_f16 v[54:57], v[58:61], v[66:69], v[54:57]
	ds_read_b128 v[58:61], v5 offset:128
	ds_read_b128 v[66:69], v5 offset:192
	s_waitcnt lgkmcnt(2)
	v_mfma_f32_16x16x32_f16 v[54:57], v[62:65], v[70:73], v[54:57]
	ds_read_b128 v[62:65], v2 offset:128
	ds_read_b128 v[70:73], v2 offset:192
	s_waitcnt lgkmcnt(1)
	v_mfma_f32_16x16x32_f16 v[54:57], v[58:61], v[62:65], v[54:57]
	ds_read_b128 v[58:61], v5 offset:256
	ds_read_b128 v[62:65], v5 offset:320
	s_waitcnt lgkmcnt(2)
	v_mfma_f32_16x16x32_f16 v[54:57], v[66:69], v[70:73], v[54:57]
	ds_read_b128 v[66:69], v2 offset:256
	ds_read_b128 v[70:73], v2 offset:320
	ds_read_b128 v[74:77], v5 offset:384
	s_waitcnt lgkmcnt(2)
	v_mfma_f32_16x16x32_f16 v[54:57], v[58:61], v[66:69], v[54:57]
	ds_read_b128 v[58:61], v2 offset:384
	ds_read_b128 v[66:69], v2 offset:448
	ds_read_b128 v[78:81], v5 offset:448
	s_waitcnt lgkmcnt(0)
	s_barrier
	s_waitcnt vmcnt(17)
	ds_write_b128 v4, v[136:139]
	s_waitcnt vmcnt(16)
	ds_write_b128 v6, v[140:143]
	s_waitcnt vmcnt(15)
	ds_write_b128 v8, v[144:147]
	s_waitcnt vmcnt(14)
	ds_write_b128 v10, v[148:151]
	s_waitcnt vmcnt(13)
	ds_write_b128 v12, v[152:155]
	s_waitcnt vmcnt(12)
	ds_write_b128 v14, v[156:159]
	s_waitcnt lgkmcnt(0)
	s_barrier
	global_load_dwordx4 v[136:139], v[18:19], off offset:3072
	global_load_dwordx4 v[140:143], v[16:17], off offset:3072
	global_load_dwordx4 v[144:147], v[20:21], off offset:3072
	global_load_dwordx4 v[148:151], v[22:23], off offset:3072
	global_load_dwordx4 v[152:155], v[24:25], off offset:3072
	global_load_dwordx4 v[156:159], v[26:27], off offset:3072
	v_mfma_f32_16x16x32_f16 v[54:57], v[62:65], v[70:73], v[54:57]
	v_mfma_f32_16x16x32_f16 v[54:57], v[74:77], v[58:61], v[54:57]
	ds_read_b128 v[58:61], v5
	v_mfma_f32_16x16x32_f16 v[54:57], v[78:81], v[66:69], v[54:57]
	ds_read_b128 v[62:65], v5 offset:64
	ds_read_b128 v[66:69], v2
	ds_read_b128 v[70:73], v2 offset:64
	s_waitcnt lgkmcnt(1)
	v_mfma_f32_16x16x32_f16 v[54:57], v[58:61], v[66:69], v[54:57]
	ds_read_b128 v[58:61], v5 offset:128
	ds_read_b128 v[66:69], v5 offset:192
	s_waitcnt lgkmcnt(2)
	v_mfma_f32_16x16x32_f16 v[54:57], v[62:65], v[70:73], v[54:57]
	ds_read_b128 v[62:65], v2 offset:128
	ds_read_b128 v[70:73], v2 offset:192
	s_waitcnt lgkmcnt(1)
	v_mfma_f32_16x16x32_f16 v[54:57], v[58:61], v[62:65], v[54:57]
	ds_read_b128 v[58:61], v5 offset:256
	ds_read_b128 v[62:65], v5 offset:320
	s_waitcnt lgkmcnt(2)
	v_mfma_f32_16x16x32_f16 v[54:57], v[66:69], v[70:73], v[54:57]
	ds_read_b128 v[66:69], v2 offset:256
	ds_read_b128 v[70:73], v2 offset:320
	ds_read_b128 v[74:77], v5 offset:384
	s_waitcnt lgkmcnt(2)
	v_mfma_f32_16x16x32_f16 v[54:57], v[58:61], v[66:69], v[54:57]
	ds_read_b128 v[58:61], v2 offset:384
	ds_read_b128 v[66:69], v2 offset:448
	ds_read_b128 v[78:81], v5 offset:448
	s_waitcnt lgkmcnt(0)
	s_barrier
	s_waitcnt vmcnt(17)
	ds_write_b128 v4, v[178:181]
	s_waitcnt vmcnt(16)
	ds_write_b128 v6, v[182:185]
	s_waitcnt vmcnt(15)
	ds_write_b128 v8, v[186:189]
	s_waitcnt vmcnt(14)
	ds_write_b128 v10, v[190:193]
	s_waitcnt vmcnt(13)
	ds_write_b128 v12, v[194:197]
	s_waitcnt vmcnt(12)
	ds_write_b128 v14, v[198:201]
	s_waitcnt lgkmcnt(0)
	s_barrier
	global_load_dwordx4 v[178:181], v[18:19], off offset:3584
	global_load_dwordx4 v[182:185], v[16:17], off offset:3584
	global_load_dwordx4 v[186:189], v[20:21], off offset:3584
	global_load_dwordx4 v[190:193], v[22:23], off offset:3584
	global_load_dwordx4 v[194:197], v[24:25], off offset:3584
	global_load_dwordx4 v[198:201], v[26:27], off offset:3584
	v_mfma_f32_16x16x32_f16 v[54:57], v[62:65], v[70:73], v[54:57]
	v_mfma_f32_16x16x32_f16 v[54:57], v[74:77], v[58:61], v[54:57]
	ds_read_b128 v[58:61], v5
	v_mfma_f32_16x16x32_f16 v[54:57], v[78:81], v[66:69], v[54:57]
	ds_read_b128 v[62:65], v5 offset:64
	ds_read_b128 v[66:69], v2
	ds_read_b128 v[70:73], v2 offset:64
	s_waitcnt lgkmcnt(1)
	v_mfma_f32_16x16x32_f16 v[54:57], v[58:61], v[66:69], v[54:57]
	ds_read_b128 v[58:61], v5 offset:128
	ds_read_b128 v[66:69], v5 offset:192
	s_waitcnt lgkmcnt(2)
	v_mfma_f32_16x16x32_f16 v[54:57], v[62:65], v[70:73], v[54:57]
	ds_read_b128 v[62:65], v2 offset:128
	ds_read_b128 v[70:73], v2 offset:192
	s_waitcnt lgkmcnt(1)
	v_mfma_f32_16x16x32_f16 v[54:57], v[58:61], v[62:65], v[54:57]
	ds_read_b128 v[58:61], v5 offset:256
	ds_read_b128 v[62:65], v5 offset:320
	s_waitcnt lgkmcnt(2)
	v_mfma_f32_16x16x32_f16 v[54:57], v[66:69], v[70:73], v[54:57]
	ds_read_b128 v[66:69], v2 offset:256
	ds_read_b128 v[70:73], v2 offset:320
	ds_read_b128 v[74:77], v5 offset:384
	s_waitcnt lgkmcnt(2)
	v_mfma_f32_16x16x32_f16 v[54:57], v[58:61], v[66:69], v[54:57]
	ds_read_b128 v[58:61], v2 offset:384
	ds_read_b128 v[66:69], v2 offset:448
	ds_read_b128 v[78:81], v5 offset:448
	s_waitcnt lgkmcnt(0)
	s_barrier
	s_waitcnt vmcnt(17)
	ds_write_b128 v4, v[206:209]
	s_waitcnt vmcnt(16)
	ds_write_b128 v6, v[210:213]
	s_waitcnt vmcnt(15)
	ds_write_b128 v8, v[214:217]
	s_waitcnt vmcnt(14)
	ds_write_b128 v10, v[218:221]
	s_waitcnt vmcnt(13)
	ds_write_b128 v12, v[120:123]
	s_waitcnt vmcnt(12)
	ds_write_b128 v14, v[124:127]
	s_waitcnt lgkmcnt(0)
	s_barrier
	global_load_dwordx4 v[206:209], v[128:129], off
	global_load_dwordx4 v[210:213], v[130:131], off
	global_load_dwordx4 v[214:217], v[132:133], off
	global_load_dwordx4 v[218:221], v[106:107], off
	global_load_dwordx4 v[120:123], v[108:109], off
	global_load_dwordx4 v[124:127], v[110:111], off
	v_mfma_f32_16x16x32_f16 v[54:57], v[62:65], v[70:73], v[54:57]
	v_mfma_f32_16x16x32_f16 v[54:57], v[74:77], v[58:61], v[54:57]
	ds_read_b128 v[58:61], v5
	v_mfma_f32_16x16x32_f16 v[54:57], v[78:81], v[66:69], v[54:57]
	ds_read_b128 v[62:65], v2
	ds_read_b128 v[66:69], v2 offset:64
	ds_read_b128 v[70:73], v5 offset:64
	ds_read_b128 v[74:77], v2 offset:128
	ds_read_b128 v[78:81], v2 offset:192
	ds_read_b128 v[82:85], v5 offset:128
	ds_read_b128 v[86:89], v5 offset:192
	s_waitcnt lgkmcnt(6)
	v_mfma_f32_16x16x32_f16 v[54:57], v[58:61], v[62:65], v[54:57]
	ds_read_b128 v[58:61], v2 offset:256
	ds_read_b128 v[62:65], v2 offset:320
	ds_read_b128 v[90:93], v5 offset:256
	ds_read_b128 v[94:97], v5 offset:320
	s_waitcnt lgkmcnt(8)
	v_mfma_f32_16x16x32_f16 v[54:57], v[70:73], v[66:69], v[54:57]
	ds_read_b128 v[66:69], v2 offset:384
	ds_read_b128 v[70:73], v2 offset:448
	ds_read_b128 v[98:101], v5 offset:384
	ds_read_b128 v[102:105], v5 offset:448
	s_waitcnt lgkmcnt(0)
	s_barrier
	s_waitcnt vmcnt(17)
	ds_write_b128 v4, v[136:139]
	s_waitcnt vmcnt(16)
	ds_write_b128 v6, v[140:143]
	s_waitcnt vmcnt(15)
	ds_write_b128 v8, v[144:147]
	s_waitcnt vmcnt(14)
	ds_write_b128 v10, v[148:151]
	s_waitcnt vmcnt(13)
	ds_write_b128 v12, v[152:155]
	s_waitcnt vmcnt(12)
	ds_write_b128 v14, v[156:159]
	s_waitcnt lgkmcnt(0)
	s_barrier
	global_load_dwordx4 v[136:139], v[128:129], off offset:512
	global_load_dwordx4 v[140:143], v[130:131], off offset:512
	global_load_dwordx4 v[144:147], v[132:133], off offset:512
	global_load_dwordx4 v[148:151], v[106:107], off offset:512
	global_load_dwordx4 v[152:155], v[108:109], off offset:512
	global_load_dwordx4 v[156:159], v[110:111], off offset:512
	v_mfma_f32_16x16x32_f16 v[54:57], v[82:85], v[74:77], v[54:57]
	v_mfma_f32_16x16x32_f16 v[54:57], v[86:89], v[78:81], v[54:57]
	v_add_co_u32_e32 v78, vcc, s24, v18
	v_mfma_f32_16x16x32_f16 v[54:57], v[90:93], v[58:61], v[54:57]
	s_nop 0
	v_addc_co_u32_e32 v79, vcc, 0, v19, vcc
	v_add_co_u32_e32 v80, vcc, s24, v26
	v_mfma_f32_16x16x32_f16 v[54:57], v[94:97], v[62:65], v[54:57]
	s_nop 0
	v_addc_co_u32_e32 v81, vcc, 0, v27, vcc
	v_add_co_u32_e32 v82, vcc, s24, v24
	v_mfma_f32_16x16x32_f16 v[54:57], v[98:101], v[66:69], v[54:57]
	s_nop 0
	v_addc_co_u32_e32 v83, vcc, 0, v25, vcc
	ds_read_b128 v[24:27], v5
	v_mfma_f32_16x16x32_f16 v[54:57], v[102:105], v[70:73], v[54:57]
	ds_read_b128 v[58:61], v2
	ds_read_b128 v[62:65], v5 offset:64
	v_add_co_u32_e32 v84, vcc, s24, v22
	ds_read_b128 v[66:69], v2 offset:64
	s_nop 0
	v_addc_co_u32_e32 v85, vcc, 0, v23, vcc
	s_waitcnt lgkmcnt(2)
	v_mfma_f32_16x16x32_f16 v[22:25], v[24:27], v[58:61], v[54:57]
	s_nop 2
	ds_read_b128 v[54:57], v5 offset:128
	ds_read_b128 v[58:61], v2 offset:128
	ds_read_b128 v[70:73], v5 offset:192
	v_add_co_u32_e32 v86, vcc, s24, v20
	s_waitcnt lgkmcnt(3)
	v_mfma_f32_16x16x32_f16 v[22:25], v[62:65], v[66:69], v[22:25]
	v_addc_co_u32_e32 v87, vcc, 0, v21, vcc
	ds_read_b128 v[18:21], v2 offset:192
	s_waitcnt lgkmcnt(2)
	v_mfma_f32_16x16x32_f16 v[22:25], v[54:57], v[58:61], v[22:25]
	ds_read_b128 v[54:57], v2 offset:256
	ds_read_b128 v[58:61], v5 offset:256
	ds_read_b128 v[62:65], v5 offset:320
	v_add_co_u32_e32 v88, vcc, s24, v16
	s_waitcnt lgkmcnt(3)
	v_mfma_f32_16x16x32_f16 v[18:21], v[70:73], v[18:21], v[22:25]
	v_addc_co_u32_e32 v89, vcc, 0, v17, vcc
	s_nop 1
	ds_read_b128 v[22:25], v2 offset:320
	ds_read_b128 v[66:69], v5 offset:384
	s_waitcnt lgkmcnt(3)
	v_mfma_f32_16x16x32_f16 v[16:19], v[58:61], v[54:57], v[18:21]
	ds_read_b128 v[54:57], v2 offset:384
	ds_read_b128 v[58:61], v2 offset:448
	ds_read_b128 v[70:73], v5 offset:448
	s_waitcnt lgkmcnt(0)
	s_barrier
	v_mfma_f32_16x16x32_f16 v[16:19], v[62:65], v[22:25], v[16:19]
	s_waitcnt vmcnt(17)
	ds_write_b128 v4, v[178:181]
	s_waitcnt vmcnt(16)
	ds_write_b128 v6, v[182:185]
	s_waitcnt vmcnt(15)
	ds_write_b128 v8, v[186:189]
	s_waitcnt vmcnt(14)
	ds_write_b128 v10, v[190:193]
	s_waitcnt vmcnt(13)
	ds_write_b128 v12, v[194:197]
	s_waitcnt vmcnt(12)
	ds_write_b128 v14, v[198:201]
	s_waitcnt lgkmcnt(0)
	s_barrier
	global_load_dwordx4 v[178:181], v[128:129], off offset:1024
	global_load_dwordx4 v[182:185], v[130:131], off offset:1024
	global_load_dwordx4 v[186:189], v[132:133], off offset:1024
	global_load_dwordx4 v[190:193], v[106:107], off offset:1024
	global_load_dwordx4 v[194:197], v[108:109], off offset:1024
	global_load_dwordx4 v[198:201], v[110:111], off offset:1024
	ds_read_b128 v[46:49], v5
	v_mfma_f32_16x16x32_f16 v[16:19], v[66:69], v[54:57], v[16:19]
	v_cmp_gt_u32_e32 vcc, 16, v28
	v_mfma_f32_16x16x32_f16 v[16:19], v[70:73], v[58:61], v[16:19]
	ds_read_b128 v[50:53], v5 offset:64
	ds_read_b128 v[54:57], v2
	ds_read_b128 v[58:61], v2 offset:64
	s_waitcnt lgkmcnt(1)
	v_mfma_f32_16x16x32_f16 v[16:19], v[46:49], v[54:57], v[16:19]
	ds_read_b128 v[46:49], v5 offset:128
	ds_read_b128 v[54:57], v5 offset:192
	s_waitcnt lgkmcnt(2)
	v_mfma_f32_16x16x32_f16 v[16:19], v[50:53], v[58:61], v[16:19]
	ds_read_b128 v[50:53], v2 offset:128
	ds_read_b128 v[58:61], v2 offset:192
	s_waitcnt lgkmcnt(1)
	v_mfma_f32_16x16x32_f16 v[16:19], v[46:49], v[50:53], v[16:19]
	ds_read_b128 v[46:49], v5 offset:256
	ds_read_b128 v[50:53], v5 offset:320
	s_waitcnt lgkmcnt(2)
	v_mfma_f32_16x16x32_f16 v[16:19], v[54:57], v[58:61], v[16:19]
	ds_read_b128 v[54:57], v2 offset:256
	ds_read_b128 v[58:61], v2 offset:320
	ds_read_b128 v[62:65], v5 offset:384
	s_waitcnt lgkmcnt(2)
	v_mfma_f32_16x16x32_f16 v[16:19], v[46:49], v[54:57], v[16:19]
	ds_read_b128 v[46:49], v2 offset:384
	ds_read_b128 v[54:57], v2 offset:448
	ds_read_b128 v[66:69], v5 offset:448
	s_waitcnt lgkmcnt(0)
	s_barrier
	s_waitcnt vmcnt(17)
	ds_write_b128 v4, v[206:209]
	s_waitcnt vmcnt(16)
	ds_write_b128 v6, v[210:213]
	s_waitcnt vmcnt(15)
	ds_write_b128 v8, v[214:217]
	s_waitcnt vmcnt(14)
	ds_write_b128 v10, v[218:221]
	s_waitcnt vmcnt(13)
	ds_write_b128 v12, v[120:123]
	s_waitcnt vmcnt(12)
	ds_write_b128 v14, v[124:127]
	s_waitcnt lgkmcnt(0)
	s_barrier
	v_mfma_f32_16x16x32_f16 v[16:19], v[50:53], v[58:61], v[16:19]
	v_mfma_f32_16x16x32_f16 v[16:19], v[62:65], v[46:49], v[16:19]
	ds_read_b128 v[46:49], v5
	v_mfma_f32_16x16x32_f16 v[16:19], v[66:69], v[54:57], v[16:19]
	ds_read_b128 v[50:53], v5 offset:64
	ds_read_b128 v[54:57], v2
	ds_read_b128 v[58:61], v2 offset:64
	s_waitcnt lgkmcnt(1)
	v_mfma_f32_16x16x32_f16 v[16:19], v[46:49], v[54:57], v[16:19]
	ds_read_b128 v[46:49], v5 offset:128
	ds_read_b128 v[54:57], v5 offset:192
	s_waitcnt lgkmcnt(2)
	v_mfma_f32_16x16x32_f16 v[16:19], v[50:53], v[58:61], v[16:19]
	ds_read_b128 v[50:53], v2 offset:128
	ds_read_b128 v[58:61], v2 offset:192
	ds_read_b128 v[62:65], v5 offset:256
	s_waitcnt lgkmcnt(2)
	v_mfma_f32_16x16x32_f16 v[16:19], v[46:49], v[50:53], v[16:19]
	ds_read_b128 v[46:49], v2 offset:256
	ds_read_b128 v[50:53], v2 offset:320
	ds_read_b128 v[66:69], v5 offset:320
	s_waitcnt lgkmcnt(4)
	v_mfma_f32_16x16x32_f16 v[16:19], v[54:57], v[58:61], v[16:19]
	ds_read_b128 v[54:57], v2 offset:384
	ds_read_b128 v[58:61], v2 offset:448
	ds_read_b128 v[70:73], v5 offset:384
	ds_read_b128 v[74:77], v5 offset:448
	s_waitcnt lgkmcnt(0)
	s_barrier
	s_waitcnt vmcnt(11)
	ds_write_b128 v4, v[136:139]
	s_waitcnt vmcnt(10)
	ds_write_b128 v6, v[140:143]
	s_waitcnt vmcnt(9)
	ds_write_b128 v8, v[144:147]
	s_waitcnt vmcnt(8)
	ds_write_b128 v10, v[148:151]
	s_waitcnt vmcnt(7)
	ds_write_b128 v12, v[152:155]
	s_waitcnt vmcnt(6)
	ds_write_b128 v14, v[156:159]
	s_waitcnt lgkmcnt(0)
	s_barrier
	v_mfma_f32_16x16x32_f16 v[16:19], v[62:65], v[46:49], v[16:19]
	ds_read_b128 v[46:49], v5
	v_mfma_f32_16x16x32_f16 v[16:19], v[66:69], v[50:53], v[16:19]
	v_mfma_f32_16x16x32_f16 v[16:19], v[70:73], v[54:57], v[16:19]
	ds_read_b128 v[50:53], v2
	ds_read_b128 v[54:57], v5 offset:64
	v_mfma_f32_16x16x32_f16 v[16:19], v[74:77], v[58:61], v[16:19]
	ds_read_b128 v[58:61], v2 offset:64
	ds_read_b128 v[62:65], v5 offset:128
	s_waitcnt lgkmcnt(3)
	v_mfma_f32_16x16x32_f16 v[16:19], v[46:49], v[50:53], v[16:19]
	ds_read_b128 v[46:49], v2 offset:128
	ds_read_b128 v[50:53], v5 offset:192
	s_waitcnt lgkmcnt(3)
	v_mfma_f32_16x16x32_f16 v[16:19], v[54:57], v[58:61], v[16:19]
	ds_read_b128 v[54:57], v2 offset:192
	ds_read_b128 v[58:61], v5 offset:256
	s_waitcnt lgkmcnt(3)
	v_mfma_f32_16x16x32_f16 v[16:19], v[62:65], v[46:49], v[16:19]
	ds_read_b128 v[46:49], v2 offset:256
	ds_read_b128 v[62:65], v2 offset:320
	ds_read_b128 v[66:69], v5 offset:320
	s_waitcnt lgkmcnt(4)
	v_mfma_f32_16x16x32_f16 v[16:19], v[50:53], v[54:57], v[16:19]
	ds_read_b128 v[50:53], v2 offset:384
	ds_read_b128 v[54:57], v2 offset:448
	ds_read_b128 v[70:73], v5 offset:384
	ds_read_b128 v[74:77], v5 offset:448
	s_waitcnt lgkmcnt(0)
	s_barrier
	v_mfma_f32_16x16x32_f16 v[16:19], v[58:61], v[46:49], v[16:19]
	s_waitcnt vmcnt(5)
	ds_write_b128 v4, v[178:181]
	s_waitcnt vmcnt(4)
	ds_write_b128 v6, v[182:185]
	s_waitcnt vmcnt(3)
	ds_write_b128 v8, v[186:189]
	s_waitcnt vmcnt(2)
	ds_write_b128 v10, v[190:193]
	s_waitcnt vmcnt(1)
	ds_write_b128 v12, v[194:197]
	s_waitcnt vmcnt(0)
	ds_write_b128 v14, v[198:201]
	v_mfma_f32_16x16x32_f16 v[16:19], v[66:69], v[62:65], v[16:19]
	s_waitcnt lgkmcnt(0)
	s_barrier
	ds_read_b128 v[6:9], v5
	v_mfma_f32_16x16x32_f16 v[10:13], v[70:73], v[50:53], v[16:19]
	s_nop 3
	ds_read_b128 v[14:17], v2
	ds_read_b128 v[18:21], v5 offset:64
	ds_read_b128 v[22:25], v2 offset:64
	ds_read_b128 v[30:33], v5 offset:128
	v_add_u32_e32 v26, s5, v3
	v_mfma_f32_16x16x32_f16 v[10:13], v[74:77], v[54:57], v[10:13]
	v_lshlrev_b64 v[34:35], 10, v[0:1]
	v_ashrrev_i32_e32 v27, 31, v26
	v_lshl_add_u64 v[34:35], v[34:35], 0, v[26:27]
	s_waitcnt lgkmcnt(3)
	v_mfma_f32_16x16x32_f16 v[6:9], v[6:9], v[14:17], v[10:13]
	s_nop 2
	ds_read_b128 v[10:13], v2 offset:128
	ds_read_b128 v[14:17], v5 offset:192
	v_lshlrev_b64 v[26:27], 2, v[26:27]
	v_lshl_add_u64 v[36:37], v[34:35], 2, s[38:39]
	s_waitcnt lgkmcnt(3)
	v_mfma_f32_16x16x32_f16 v[6:9], v[18:21], v[22:25], v[6:9]
	ds_read_b128 v[18:21], v2 offset:192
	ds_read_b128 v[22:25], v5 offset:256
	s_waitcnt lgkmcnt(3)
	v_mfma_f32_16x16x32_f16 v[6:9], v[30:33], v[10:13], v[6:9]
	ds_read_b128 v[10:13], v2 offset:256
	ds_read_b128 v[30:33], v5 offset:320
	s_waitcnt lgkmcnt(3)
	v_mfma_f32_16x16x32_f16 v[6:9], v[14:17], v[18:21], v[6:9]
	ds_read_b128 v[14:17], v2 offset:320
	ds_read_b128 v[18:21], v5 offset:384
	s_waitcnt lgkmcnt(3)
	v_mfma_f32_16x16x32_f16 v[6:9], v[22:25], v[10:13], v[6:9]
	ds_read_b128 v[10:13], v2 offset:384
	v_lshl_add_u64 v[22:23], s[0:1], 0, v[26:27]
	s_waitcnt lgkmcnt(2)
	v_mfma_f32_16x16x32_f16 v[6:9], v[30:33], v[14:17], v[6:9]
	ds_read_b128 v[14:17], v2 offset:448
	ds_read_b128 v[2:5], v5 offset:448
	global_load_dwordx4 v[22:25], v[22:23], off
	s_waitcnt lgkmcnt(2)
	v_mfma_f32_16x16x32_f16 v[6:9], v[18:21], v[10:13], v[6:9]
	global_load_dwordx4 v[10:13], v[36:37], off
	v_lshl_add_u64 v[18:19], s[2:3], 0, v[26:27]
	s_waitcnt lgkmcnt(0)
	v_mfma_f32_16x16x32_f16 v[2:5], v[2:5], v[14:17], v[6:9]
	s_waitcnt vmcnt(1)
	s_nop 2
	v_pk_mul_f32 v[6:7], v[24:25], 0.5 op_sel_hi:[1,0]
	v_pk_mul_f32 v[8:9], v[22:23], 0.5 op_sel_hi:[1,0]
	s_waitcnt vmcnt(0)
	s_nop 0
	v_pk_fma_f32 v[6:7], v[4:5], v[6:7], v[12:13]
	v_pk_fma_f32 v[4:5], v[2:3], v[8:9], v[10:11]
	global_store_dwordx4 v[36:37], v[4:7], off
	global_load_dwordx4 v[8:11], v[18:19], off
	v_mul_f32_e32 v2, v5, v5
	v_mul_f32_e32 v3, v7, v7
	v_fmac_f32_e32 v2, v4, v4
	v_fmac_f32_e32 v3, v6, v6
	v_add_f32_e32 v2, v2, v3
	ds_bpermute_b32 v3, v134, v2
	v_lshl_add_u64 v[12:13], v[34:35], 1, s[42:43]
	s_waitcnt lgkmcnt(0)
	v_add_f32_e32 v2, v2, v3
	ds_bpermute_b32 v3, v135, v2
	s_waitcnt vmcnt(0)
	v_pk_mul_f32 v[6:7], v[10:11], v[6:7]
	v_pk_mul_f32 v[4:5], v[8:9], v[4:5]
	s_nop 0
	v_cvt_pk_f16_f32 v4, v4, v5
	v_cvt_pk_f16_f32 v5, v6, v7
	global_store_dwordx2 v[12:13], v[4:5], off
	s_and_saveexec_b64 s[4:5], vcc
	s_cbranch_execz .LBB0_1243
	v_lshlrev_b32_e32 v0, 2, v0
	s_waitcnt lgkmcnt(0)
	v_add_f32_e32 v2, v2, v3
	global_atomic_add_f32 v0, v2, s[12:13]
	s_branch .LBB0_1243
